# rmsnorm (PH0 and PH7): the eight gain loads hoisted above the row-load wait into free registers; the per-chunk vmcnt(0) that also drained the stores is gone
# baseline (speedup 1.0000x reference)
; DI void rms_rows4_to_bf16(const float* xb, size_t xstride, const float* g, bf16_t* ob, size_t ostride, int lane) {
;     f32x4 v[4][8]; float ss[4];
; #pragma unroll
;     for (int r = 0; r < 4; ++r)
; #pragma unroll
;         for (int j = 0; j < 8; ++j) v[r][j] = ((const f32x4*)(xb + r * xstride))[lane + 64 * j];
; #pragma unroll
;     for (int r = 0; r < 4; ++r) { float s = 0.f;
; #pragma unroll
;         for (int j = 0; j < 8; ++j) s += (v[r][j].x * v[r][j].x + v[r][j].y * v[r][j].y) + (v[r][j].z * v[r][j].z + v[r][j].w * v[r][j].w);
;         ss[r] = rsqrtf(wave_sum(s) * (1.f / D_) + EPS_); }
.LBB0_75:
	s_and_b64 vcc, exec, s[2:3]
	s_cbranch_vccz .LBB0_70
	s_ashr_i32 s1, s0, 31
	s_lshl_b64 s[2:3], s[0:1], 13
	s_add_u32 s2, s5, s2
	s_addc_u32 s3, s4, s3
	global_load_dwordx4 v[124:127], v133, s[2:3]
	global_load_dwordx4 v[104:107], v133, s[2:3] offset:1024
	global_load_dwordx4 v[80:83], v133, s[2:3] offset:2048
	global_load_dwordx4 v[64:67], v133, s[2:3] offset:3072
	global_load_dwordx4 v[56:59], v151, s[2:3]
	global_load_dwordx4 v[40:43], v153, s[2:3]
	global_load_dwordx4 v[24:27], v155, s[2:3]
	global_load_dwordx4 v[8:11], v157, s[2:3]
	s_lshl_b64 s[6:7], s[20:21], 2
	s_add_u32 s2, s2, s6
	s_addc_u32 s3, s3, s7
	global_load_dwordx4 v[120:123], v133, s[2:3]
	global_load_dwordx4 v[108:111], v133, s[2:3] offset:1024
	global_load_dwordx4 v[92:95], v133, s[2:3] offset:2048
	global_load_dwordx4 v[68:71], v133, s[2:3] offset:3072
	global_load_dwordx4 v[60:63], v151, s[2:3]
	global_load_dwordx4 v[44:47], v153, s[2:3]
	global_load_dwordx4 v[28:31], v155, s[2:3]
	global_load_dwordx4 v[12:15], v157, s[2:3]
	v_and_b32_e32 v128, 64, v189
	v_add_u32_e32 v128, 64, v128
	v_xor_b32_e32 v129, 1, v189
	v_cmp_lt_i32_e32 vcc, v129, v128
	s_add_u32 s2, s2, s80
	s_addc_u32 s3, s3, s81
	v_cndmask_b32_e32 v129, v189, v129, vcc
	v_lshlrev_b32_e32 v130, 2, v129
	v_xor_b32_e32 v129, 2, v189
	v_cmp_lt_i32_e32 vcc, v129, v128
	global_load_dwordx4 v[116:119], v133, s[2:3]
	global_load_dwordx4 v[100:103], v133, s[2:3] offset:1024
	global_load_dwordx4 v[84:87], v133, s[2:3] offset:2048
	global_load_dwordx4 v[72:75], v133, s[2:3] offset:3072
	global_load_dwordx4 v[52:55], v151, s[2:3]
	global_load_dwordx4 v[36:39], v153, s[2:3]
	global_load_dwordx4 v[20:23], v155, s[2:3]
	global_load_dwordx4 v[4:7], v157, s[2:3]
	v_cndmask_b32_e32 v129, v189, v129, vcc
	v_lshlrev_b32_e32 v131, 2, v129
	v_xor_b32_e32 v129, 4, v189
	v_cmp_lt_i32_e32 vcc, v129, v128
	s_add_u32 s2, s2, s80
	s_addc_u32 s3, s3, s81
	v_cndmask_b32_e32 v129, v189, v129, vcc
	v_lshlrev_b32_e32 v154, 2, v129
	v_xor_b32_e32 v129, 8, v189
	v_cmp_lt_i32_e32 vcc, v129, v128
	global_load_dwordx4 v[112:115], v133, s[2:3]
	global_load_dwordx4 v[96:99], v133, s[2:3] offset:1024
	global_load_dwordx4 v[88:91], v133, s[2:3] offset:2048
	global_load_dwordx4 v[76:79], v133, s[2:3] offset:3072
	global_load_dwordx4 v[48:51], v151, s[2:3]
	global_load_dwordx4 v[32:35], v153, s[2:3]
	global_load_dwordx4 v[16:19], v155, s[2:3]
	global_load_dwordx4 v[0:3], v157, s[2:3]
	v_cndmask_b32_e32 v129, v189, v129, vcc
	v_lshlrev_b32_e32 v156, 2, v129
	v_xor_b32_e32 v129, 16, v189
	v_cmp_lt_i32_e32 vcc, v129, v128
	s_lshl_b64 s[2:3], s[0:1], 12
	global_load_dwordx4 v[200:203], v[134:135], off
	global_load_dwordx4 v[204:207], v[134:135], off offset:1024
	global_load_dwordx4 v[208:211], v[134:135], off offset:2048
	global_load_dwordx4 v[212:215], v[134:135], off offset:3072
	global_load_dwordx4 v[216:219], v[136:137], off
	global_load_dwordx4 v[220:223], v[138:139], off
	global_load_dwordx4 v[224:227], v[140:141], off
	global_load_dwordx4 v[228:231], v[142:143], off
	s_waitcnt vmcnt(0)
	v_mov_b32_e32 v170, v125
	v_cndmask_b32_e32 v129, v189, v129, vcc
	v_lshlrev_b32_e32 v158, 2, v129
	v_xor_b32_e32 v129, 32, v189
	v_cmp_lt_i32_e32 vcc, v129, v128
	v_mov_b32_e32 v171, v105
	v_pk_mul_f32 v[170:171], v[170:171], v[170:171]
	v_cndmask_b32_e32 v128, v189, v129, vcc
	v_lshlrev_b32_e32 v159, 2, v128
	v_mov_b32_e32 v128, v124
	v_mov_b32_e32 v129, v104
	v_mov_b32_e32 v172, v127
	v_mov_b32_e32 v173, v107
	v_pk_fma_f32 v[128:129], v[128:129], v[128:129], v[170:171]
	v_mov_b32_e32 v170, v126
	v_mov_b32_e32 v171, v106
	v_pk_mul_f32 v[172:173], v[172:173], v[172:173]
	v_mul_f32_e32 v150, v56, v56
	v_pk_fma_f32 v[170:171], v[170:171], v[170:171], v[172:173]
	v_pk_mul_f32 v[172:173], v[80:81], v[80:81]
	v_pk_add_f32 v[128:129], v[128:129], v[170:171]
	v_pk_mul_f32 v[170:171], v[82:83], v[82:83]
	v_mul_f32_e32 v152, v57, v57
	v_pk_mov_b32 v[174:175], v[172:173], v[170:171] op_sel:[1,0]
	v_mov_b32_e32 v173, v171
	v_pk_add_f32 v[170:171], v[174:175], v[172:173]
	v_pk_add_f32 v[128:129], v[128:129], v[128:129] op_sel:[0,1] op_sel_hi:[1,0]
	v_pk_add_f32 v[170:171], v[170:171], v[170:171] op_sel:[0,1] op_sel_hi:[1,0]
	v_mov_b32_e32 v129, v150
	v_mov_b32_e32 v171, v152
	v_mul_f32_e32 v150, v65, v65
	v_pk_add_f32 v[128:129], v[128:129], v[170:171]
	v_pk_fma_f32 v[170:171], v[64:65], v[64:65], v[150:151] op_sel_hi:[1,1,0]
	v_mul_f32_e32 v150, v67, v67
	v_mul_f32_e32 v166, v58, v58
	v_mul_f32_e32 v167, v59, v59
	v_pk_fma_f32 v[172:173], v[66:67], v[66:67], v[150:151] op_sel_hi:[1,1,0]
	v_mov_b32_e32 v171, v166
	v_mov_b32_e32 v173, v167
	v_pk_add_f32 v[170:171], v[170:171], v[172:173]
	v_pk_mul_f32 v[172:173], v[40:41], v[40:41]
	v_pk_add_f32 v[128:129], v[128:129], v[170:171]
	v_pk_mul_f32 v[170:171], v[42:43], v[42:43]
	v_mul_f32_e32 v150, v8, v8
	v_pk_mov_b32 v[174:175], v[172:173], v[170:171] op_sel:[1,0]
	v_mov_b32_e32 v173, v171
	v_pk_add_f32 v[170:171], v[174:175], v[172:173]
	v_mul_f32_e32 v152, v9, v9
	v_pk_add_f32 v[128:129], v[128:129], v[128:129] op_sel:[0,1] op_sel_hi:[1,0]
	v_pk_add_f32 v[170:171], v[170:171], v[170:171] op_sel:[0,1] op_sel_hi:[1,0]
	v_mov_b32_e32 v129, v150
	v_mov_b32_e32 v171, v152
	v_mul_f32_e32 v150, v25, v25
	v_pk_add_f32 v[128:129], v[128:129], v[170:171]
	v_pk_fma_f32 v[170:171], v[24:25], v[24:25], v[150:151] op_sel_hi:[1,1,0]
	v_mul_f32_e32 v150, v27, v27
	v_mul_f32_e32 v166, v10, v10
	v_mul_f32_e32 v167, v11, v11
	v_pk_fma_f32 v[172:173], v[26:27], v[26:27], v[150:151] op_sel_hi:[1,1,0]
	v_mov_b32_e32 v171, v166
	v_mov_b32_e32 v173, v167
	v_pk_add_f32 v[170:171], v[170:171], v[172:173]
	v_mov_b32_e32 v172, v121
; DI float wave_sum(float v) {
; #pragma unroll
;     for (int o = 1; o < 64; o <<= 1) v += __shfl_xor(v, o);
;     return v;
; }
; DI void rms_rows4_to_bf16(const float* xb, size_t xstride, const float* g, bf16_t* ob, size_t ostride, int lane) {
;     f32x4 v[4][8]; float ss[4];
; #pragma unroll
;     for (int r = 0; r < 4; ++r)
; #pragma unroll
;         for (int j = 0; j < 8; ++j) v[r][j] = ((const f32x4*)(xb + r * xstride))[lane + 64 * j];
; #pragma unroll
;     for (int r = 0; r < 4; ++r) { float s = 0.f;
; #pragma unroll
;         for (int j = 0; j < 8; ++j) s += (v[r][j].x * v[r][j].x + v[r][j].y * v[r][j].y) + (v[r][j].z * v[r][j].z + v[r][j].w * v[r][j].w);
;         ss[r] = rsqrtf(wave_sum(s) * (1.f / D_) + EPS_); }
	v_mov_b32_e32 v173, v109
	v_pk_add_f32 v[128:129], v[128:129], v[170:171]
	v_mov_b32_e32 v170, v120
	v_mov_b32_e32 v171, v108
	v_pk_mul_f32 v[172:173], v[172:173], v[172:173]
	v_mov_b32_e32 v174, v123
	v_mov_b32_e32 v175, v111
	v_pk_fma_f32 v[170:171], v[170:171], v[170:171], v[172:173]
	v_mov_b32_e32 v172, v122
	v_mov_b32_e32 v173, v110
	v_pk_mul_f32 v[174:175], v[174:175], v[174:175]
	v_mul_f32_e32 v150, v60, v60
	v_pk_fma_f32 v[172:173], v[172:173], v[172:173], v[174:175]
	v_pk_mul_f32 v[174:175], v[92:93], v[92:93]
	v_pk_add_f32 v[170:171], v[170:171], v[172:173]
	v_pk_mul_f32 v[172:173], v[94:95], v[94:95]
	v_mul_f32_e32 v152, v61, v61
	v_pk_mov_b32 v[176:177], v[174:175], v[172:173] op_sel:[1,0]
	v_mov_b32_e32 v175, v173
	v_pk_add_f32 v[172:173], v[176:177], v[174:175]
	v_pk_add_f32 v[170:171], v[170:171], v[170:171] op_sel:[0,1] op_sel_hi:[1,0]
	v_pk_add_f32 v[172:173], v[172:173], v[172:173] op_sel:[0,1] op_sel_hi:[1,0]
	v_mov_b32_e32 v171, v150
	v_mov_b32_e32 v173, v152
	v_mul_f32_e32 v150, v69, v69
	v_pk_add_f32 v[170:171], v[170:171], v[172:173]
	v_pk_fma_f32 v[172:173], v[68:69], v[68:69], v[150:151] op_sel_hi:[1,1,0]
	v_mul_f32_e32 v150, v71, v71
	v_mul_f32_e32 v166, v62, v62
	v_mul_f32_e32 v167, v63, v63
	v_pk_fma_f32 v[174:175], v[70:71], v[70:71], v[150:151] op_sel_hi:[1,1,0]
	v_mov_b32_e32 v173, v166
	v_mov_b32_e32 v175, v167
	v_pk_add_f32 v[172:173], v[172:173], v[174:175]
	v_pk_mul_f32 v[174:175], v[44:45], v[44:45]
	v_pk_add_f32 v[170:171], v[170:171], v[172:173]
	v_pk_mul_f32 v[172:173], v[46:47], v[46:47]
	v_mul_f32_e32 v150, v12, v12
	v_pk_mov_b32 v[176:177], v[174:175], v[172:173] op_sel:[1,0]
	v_mov_b32_e32 v175, v173
	v_pk_add_f32 v[172:173], v[176:177], v[174:175]
	v_mul_f32_e32 v152, v13, v13
	v_pk_add_f32 v[170:171], v[170:171], v[170:171] op_sel:[0,1] op_sel_hi:[1,0]
	v_pk_add_f32 v[172:173], v[172:173], v[172:173] op_sel:[0,1] op_sel_hi:[1,0]
	v_mov_b32_e32 v171, v150
	v_mov_b32_e32 v173, v152
	v_mul_f32_e32 v150, v29, v29
	v_pk_add_f32 v[170:171], v[170:171], v[172:173]
	v_pk_fma_f32 v[172:173], v[28:29], v[28:29], v[150:151] op_sel_hi:[1,1,0]
	v_mul_f32_e32 v150, v31, v31
	v_mul_f32_e32 v166, v14, v14
	v_mul_f32_e32 v167, v15, v15
	v_pk_fma_f32 v[174:175], v[30:31], v[30:31], v[150:151] op_sel_hi:[1,1,0]
	v_mov_b32_e32 v173, v166
	v_mov_b32_e32 v175, v167
	v_pk_add_f32 v[172:173], v[172:173], v[174:175]
	v_mov_b32_e32 v174, v119
	v_pk_add_f32 v[170:171], v[170:171], v[172:173]
	v_mov_b32_e32 v173, v128
	v_mov_b32_e32 v172, v170
	v_mov_b32_e32 v128, v171
	v_pk_add_f32 v[128:129], v[172:173], v[128:129]
	ds_bpermute_b32 v171, v130, v129
	ds_bpermute_b32 v170, v130, v128
	v_mov_b32_e32 v172, v117
	v_mov_b32_e32 v173, v101
	v_pk_mul_f32 v[172:173], v[172:173], v[172:173]
	v_mov_b32_e32 v175, v103
	s_waitcnt lgkmcnt(0)
	v_pk_add_f32 v[128:129], v[128:129], v[170:171]
	ds_bpermute_b32 v171, v131, v129
	ds_bpermute_b32 v170, v131, v128
	v_pk_mul_f32 v[174:175], v[174:175], v[174:175]
	v_mul_f32_e32 v167, v53, v53
	v_mul_f32_e32 v168, v54, v54
	v_mul_f32_e32 v169, v55, v55
	s_waitcnt lgkmcnt(0)
	v_pk_add_f32 v[128:129], v[128:129], v[170:171]
	ds_bpermute_b32 v171, v154, v129
	ds_bpermute_b32 v170, v154, v128
	s_waitcnt lgkmcnt(0)
	v_pk_add_f32 v[128:129], v[128:129], v[170:171]
	ds_bpermute_b32 v171, v156, v129
	ds_bpermute_b32 v170, v156, v128
	s_waitcnt lgkmcnt(0)
	v_pk_add_f32 v[128:129], v[128:129], v[170:171]
	ds_bpermute_b32 v171, v158, v129
	ds_bpermute_b32 v170, v158, v128
	s_waitcnt lgkmcnt(0)
	v_pk_add_f32 v[128:129], v[128:129], v[170:171]
	ds_bpermute_b32 v171, v159, v129
	ds_bpermute_b32 v170, v159, v128
	s_waitcnt lgkmcnt(0)
	v_pk_add_f32 v[170:171], v[128:129], v[170:171]
	v_mov_b64_e32 v[128:129], s[34:35]
	v_pk_fma_f32 v[170:171], v[170:171], s[16:17], v[128:129] op_sel_hi:[1,0,0]
	s_nop 0
	v_mul_f32_e32 v150, 0x4b800000, v171
	v_cmp_gt_f32_e64 s[36:37], s97, v171
	v_cmp_gt_f32_e32 vcc, s97, v170
	s_nop 0
	v_cndmask_b32_e64 v150, v171, v150, s[36:37]
	v_rsq_f32_e32 v150, v150
	v_mov_b32_e32 v171, v100
	v_mul_f32_e32 v152, 0x45800000, v150
	v_cndmask_b32_e64 v152, v150, v152, s[36:37]
	v_mul_f32_e32 v150, 0x4b800000, v170
	v_cndmask_b32_e32 v150, v170, v150, vcc
	v_mov_b32_e32 v170, v116
	v_rsq_f32_e32 v150, v150
	v_pk_fma_f32 v[170:171], v[170:171], v[170:171], v[172:173]
	v_mov_b32_e32 v172, v118
	v_mov_b32_e32 v173, v102
	v_pk_fma_f32 v[172:173], v[172:173], v[172:173], v[174:175]
	v_pk_mul_f32 v[174:175], v[84:85], v[84:85]
	v_pk_add_f32 v[170:171], v[170:171], v[172:173]
	v_pk_mul_f32 v[172:173], v[86:87], v[86:87]
	v_mul_f32_e32 v166, 0x45800000, v150
	v_pk_mov_b32 v[176:177], v[174:175], v[172:173] op_sel:[1,0]
	v_mov_b32_e32 v175, v173
	v_pk_add_f32 v[172:173], v[176:177], v[174:175]
	v_cndmask_b32_e32 v150, v150, v166, vcc
	v_mul_f32_e32 v166, v52, v52
	v_pk_add_f32 v[170:171], v[170:171], v[170:171] op_sel:[0,1] op_sel_hi:[1,0]
	v_pk_add_f32 v[172:173], v[172:173], v[172:173] op_sel:[0,1] op_sel_hi:[1,0]
	v_mov_b32_e32 v171, v166
	v_mov_b32_e32 v173, v167
	v_pk_add_f32 v[170:171], v[170:171], v[172:173]
	v_mul_f32_e32 v172, v73, v73
	v_mul_f32_e32 v174, v75, v75
	v_pk_fma_f32 v[172:173], v[72:73], v[72:73], v[172:173] op_sel_hi:[1,1,0]
	v_pk_fma_f32 v[174:175], v[74:75], v[74:75], v[174:175] op_sel_hi:[1,1,0]
	v_mov_b32_e32 v173, v168
	v_mov_b32_e32 v175, v169
	v_pk_add_f32 v[172:173], v[172:173], v[174:175]
	v_pk_mul_f32 v[174:175], v[36:37], v[36:37]
	v_pk_add_f32 v[170:171], v[170:171], v[172:173]
	v_pk_mul_f32 v[172:173], v[38:39], v[38:39]
	v_mul_f32_e32 v166, v4, v4
	v_pk_mov_b32 v[176:177], v[174:175], v[172:173] op_sel:[1,0]
	v_mov_b32_e32 v175, v173
; DI unsigned pk2(float lo, float hi) { f32x2 v = {lo, hi}; bf16x2_t b = __builtin_convertvector(v, bf16x2_t); return __builtin_bit_cast(unsigned, b); }
; DI void rms_rows4_to_bf16(const float* xb, size_t xstride, const float* g, bf16_t* ob, size_t ostride, int lane) {
;     ...
;     for (int r = 0; r < 4; ++r) { float s = 0.f;
; #pragma unroll
;         for (int j = 0; j < 8; ++j) s += (v[r][j].x * v[r][j].x + v[r][j].y * v[r][j].y) + (v[r][j].z * v[r][j].z + v[r][j].w * v[r][j].w);
;         ss[r] = rsqrtf(wave_sum(s) * (1.f / D_) + EPS_); }
;     const f32x4* gr = (const f32x4*)g + lane;
; #pragma unroll
;     for (int j = 0; j < 8; ++j) { const f32x4 gg = gr[64 * j];
; #pragma unroll
;         for (int r = 0; r < 4; ++r) { u32x2 w; w.x = pk2(v[r][j].x * ss[r] * gg.x, v[r][j].y * ss[r] * gg.y); w.y = pk2(v[r][j].z * ss[r] * gg.z, v[r][j].w * ss[r] * gg.w);
	v_pk_add_f32 v[172:173], v[176:177], v[174:175]
	v_mul_f32_e32 v167, v5, v5
	v_pk_add_f32 v[170:171], v[170:171], v[170:171] op_sel:[0,1] op_sel_hi:[1,0]
	v_pk_add_f32 v[172:173], v[172:173], v[172:173] op_sel:[0,1] op_sel_hi:[1,0]
	v_mov_b32_e32 v171, v166
	v_mov_b32_e32 v173, v167
	v_pk_add_f32 v[170:171], v[170:171], v[172:173]
	v_mul_f32_e32 v172, v21, v21
	v_mul_f32_e32 v174, v23, v23
	v_mul_f32_e32 v168, v6, v6
	v_mul_f32_e32 v169, v7, v7
	v_pk_fma_f32 v[172:173], v[20:21], v[20:21], v[172:173] op_sel_hi:[1,1,0]
	v_pk_fma_f32 v[174:175], v[22:23], v[22:23], v[174:175] op_sel_hi:[1,1,0]
	v_mov_b32_e32 v173, v168
	v_mov_b32_e32 v175, v169
	v_pk_add_f32 v[172:173], v[172:173], v[174:175]
	v_mov_b32_e32 v174, v113
	v_mov_b32_e32 v175, v97
	v_pk_add_f32 v[170:171], v[170:171], v[172:173]
	v_mov_b32_e32 v172, v112
	v_mov_b32_e32 v173, v96
	v_pk_mul_f32 v[174:175], v[174:175], v[174:175]
	v_mov_b32_e32 v176, v115
	v_mov_b32_e32 v177, v99
	v_pk_fma_f32 v[172:173], v[172:173], v[172:173], v[174:175]
	v_mov_b32_e32 v174, v114
	v_mov_b32_e32 v175, v98
	v_pk_mul_f32 v[176:177], v[176:177], v[176:177]
	v_mul_f32_e32 v166, v48, v48
	v_pk_fma_f32 v[174:175], v[174:175], v[174:175], v[176:177]
	v_pk_mul_f32 v[176:177], v[88:89], v[88:89]
	v_pk_add_f32 v[172:173], v[172:173], v[174:175]
	v_pk_mul_f32 v[174:175], v[90:91], v[90:91]
	v_mul_f32_e32 v167, v49, v49
	v_pk_mov_b32 v[178:179], v[176:177], v[174:175] op_sel:[1,0]
	v_mov_b32_e32 v177, v175
	v_pk_add_f32 v[174:175], v[178:179], v[176:177]
	v_pk_add_f32 v[172:173], v[172:173], v[172:173] op_sel:[0,1] op_sel_hi:[1,0]
	v_pk_add_f32 v[174:175], v[174:175], v[174:175] op_sel:[0,1] op_sel_hi:[1,0]
	v_mov_b32_e32 v173, v166
	v_mov_b32_e32 v175, v167
	v_pk_add_f32 v[172:173], v[172:173], v[174:175]
	v_mul_f32_e32 v174, v77, v77
	v_mul_f32_e32 v176, v79, v79
	v_mul_f32_e32 v168, v50, v50
	v_mul_f32_e32 v169, v51, v51
	v_pk_fma_f32 v[174:175], v[76:77], v[76:77], v[174:175] op_sel_hi:[1,1,0]
	v_pk_fma_f32 v[176:177], v[78:79], v[78:79], v[176:177] op_sel_hi:[1,1,0]
	v_mov_b32_e32 v175, v168
	v_mov_b32_e32 v177, v169
	v_pk_add_f32 v[174:175], v[174:175], v[176:177]
	v_pk_mul_f32 v[176:177], v[32:33], v[32:33]
	v_pk_add_f32 v[172:173], v[172:173], v[174:175]
	v_pk_mul_f32 v[174:175], v[34:35], v[34:35]
	v_mul_f32_e32 v166, v0, v0
	v_pk_mov_b32 v[178:179], v[176:177], v[174:175] op_sel:[1,0]
	v_mov_b32_e32 v177, v175
	v_pk_add_f32 v[174:175], v[178:179], v[176:177]
	v_mul_f32_e32 v167, v1, v1
	v_pk_add_f32 v[172:173], v[172:173], v[172:173] op_sel:[0,1] op_sel_hi:[1,0]
	v_pk_add_f32 v[174:175], v[174:175], v[174:175] op_sel:[0,1] op_sel_hi:[1,0]
	v_mov_b32_e32 v173, v166
	v_mov_b32_e32 v175, v167
	v_pk_add_f32 v[172:173], v[172:173], v[174:175]
	v_mul_f32_e32 v174, v17, v17
	v_mul_f32_e32 v176, v19, v19
	v_mul_f32_e32 v168, v2, v2
	v_mul_f32_e32 v169, v3, v3
	v_pk_fma_f32 v[174:175], v[16:17], v[16:17], v[174:175] op_sel_hi:[1,1,0]
	v_pk_fma_f32 v[176:177], v[18:19], v[18:19], v[176:177] op_sel_hi:[1,1,0]
	v_mov_b32_e32 v175, v168
	v_mov_b32_e32 v177, v169
	v_pk_add_f32 v[174:175], v[174:175], v[176:177]
	v_pk_mul_f32 v[120:121], v[120:121], v[150:151] op_sel_hi:[1,0]
	v_pk_add_f32 v[172:173], v[172:173], v[174:175]
	v_mov_b32_e32 v175, v170
	v_mov_b32_e32 v174, v172
	v_mov_b32_e32 v170, v173
	v_pk_add_f32 v[170:171], v[174:175], v[170:171]
	ds_bpermute_b32 v173, v130, v171
	ds_bpermute_b32 v172, v130, v170
	v_pk_mul_f32 v[122:123], v[122:123], v[150:151] op_sel_hi:[1,0]
	v_pk_mul_f32 v[124:125], v[124:125], v[152:153] op_sel_hi:[1,0]
	v_pk_mul_f32 v[126:127], v[126:127], v[152:153] op_sel_hi:[1,0]
	v_pk_mul_f32 v[104:105], v[104:105], v[152:153] op_sel_hi:[1,0]
	s_waitcnt lgkmcnt(0)
	v_pk_add_f32 v[170:171], v[170:171], v[172:173]
	ds_bpermute_b32 v173, v131, v171
	ds_bpermute_b32 v172, v131, v170
	v_pk_mul_f32 v[106:107], v[106:107], v[152:153] op_sel_hi:[1,0]
	v_pk_mul_f32 v[80:81], v[80:81], v[152:153] op_sel_hi:[1,0]
	v_pk_mul_f32 v[82:83], v[82:83], v[152:153] op_sel_hi:[1,0]
	v_pk_mul_f32 v[64:65], v[64:65], v[152:153] op_sel_hi:[1,0]
	s_waitcnt lgkmcnt(0)
	v_pk_add_f32 v[130:131], v[170:171], v[172:173]
	ds_bpermute_b32 v171, v154, v131
	ds_bpermute_b32 v170, v154, v130
	v_pk_mul_f32 v[66:67], v[66:67], v[152:153] op_sel_hi:[1,0]
	v_pk_mul_f32 v[56:57], v[56:57], v[152:153] op_sel_hi:[1,0]
	v_pk_mul_f32 v[58:59], v[58:59], v[152:153] op_sel_hi:[1,0]
	v_pk_mul_f32 v[40:41], v[40:41], v[152:153] op_sel_hi:[1,0]
	s_waitcnt lgkmcnt(0)
	v_pk_add_f32 v[130:131], v[130:131], v[170:171]
	ds_bpermute_b32 v171, v156, v131
	ds_bpermute_b32 v170, v156, v130
	v_pk_mul_f32 v[42:43], v[42:43], v[152:153] op_sel_hi:[1,0]
	v_pk_mul_f32 v[24:25], v[24:25], v[152:153] op_sel_hi:[1,0]
	v_pk_mul_f32 v[26:27], v[26:27], v[152:153] op_sel_hi:[1,0]
	v_pk_mul_f32 v[8:9], v[8:9], v[152:153] op_sel_hi:[1,0]
	s_waitcnt lgkmcnt(0)
	v_pk_add_f32 v[130:131], v[130:131], v[170:171]
	ds_bpermute_b32 v171, v158, v131
	ds_bpermute_b32 v170, v158, v130
	v_pk_mul_f32 v[10:11], v[10:11], v[152:153] op_sel_hi:[1,0]
	s_waitcnt lgkmcnt(0)
	v_pk_add_f32 v[130:131], v[130:131], v[170:171]
	ds_bpermute_b32 v171, v159, v131
	ds_bpermute_b32 v170, v159, v130
	v_lshl_add_u64 v[158:159], v[144:145], 0, s[2:3]
	v_readlane_b32 s2, v254, 22
	v_readlane_b32 s3, v254, 23
	s_waitcnt lgkmcnt(0)
; DI unsigned pk2(float lo, float hi) { f32x2 v = {lo, hi}; bf16x2_t b = __builtin_convertvector(v, bf16x2_t); return __builtin_bit_cast(unsigned, b); }
; DI void rms_rows4_to_bf16(const float* xb, size_t xstride, const float* g, bf16_t* ob, size_t ostride, int lane) {
;     ...
;         ss[r] = rsqrtf(wave_sum(s) * (1.f / D_) + EPS_); }
;     const f32x4* gr = (const f32x4*)g + lane;
; #pragma unroll
;     for (int j = 0; j < 8; ++j) { const f32x4 gg = gr[64 * j];
; #pragma unroll
;         for (int r = 0; r < 4; ++r) { u32x2 w; w.x = pk2(v[r][j].x * ss[r] * gg.x, v[r][j].y * ss[r] * gg.y); w.y = pk2(v[r][j].z * ss[r] * gg.z, v[r][j].w * ss[r] * gg.w);
;             ((u32x2*)(ob + r * ostride))[lane + 64 * j] = w; } }
; }
	v_pk_add_f32 v[130:131], v[130:131], v[170:171]
	s_nop 0
	v_pk_fma_f32 v[128:129], v[130:131], s[16:17], v[128:129] op_sel_hi:[1,0,0]
	s_nop 0
	v_mul_f32_e32 v130, 0x4b800000, v129
	v_cmp_gt_f32_e64 s[36:37], s97, v129
	v_cmp_gt_f32_e32 vcc, s97, v128
	s_nop 0
	v_cndmask_b32_e64 v129, v129, v130, s[36:37]
	v_rsq_f32_e32 v129, v129
	s_nop 0
	v_mul_f32_e32 v130, 0x45800000, v129
	v_cndmask_b32_e64 v156, v129, v130, s[36:37]
	v_mul_f32_e32 v129, 0x4b800000, v128
	v_cndmask_b32_e32 v128, v128, v129, vcc
	v_rsq_f32_e32 v128, v128
	v_pk_mul_f32 v[116:117], v[116:117], v[156:157] op_sel_hi:[1,0]
	v_pk_mul_f32 v[118:119], v[118:119], v[156:157] op_sel_hi:[1,0]
	v_pk_mul_f32 v[100:101], v[100:101], v[156:157] op_sel_hi:[1,0]
	v_mul_f32_e32 v129, 0x45800000, v128
	v_cndmask_b32_e32 v154, v128, v129, vcc
	v_pk_mul_f32 v[112:113], v[112:113], v[154:155] op_sel_hi:[1,0]
	v_pk_mul_f32 v[114:115], v[114:115], v[154:155] op_sel_hi:[1,0]
	v_pk_mul_f32 v[102:103], v[102:103], v[156:157] op_sel_hi:[1,0]
	v_pk_mul_f32 v[96:97], v[96:97], v[154:155] op_sel_hi:[1,0]
	v_pk_mul_f32 v[98:99], v[98:99], v[154:155] op_sel_hi:[1,0]
	v_pk_mul_f32 v[52:53], v[52:53], v[156:157] op_sel_hi:[1,0]
	v_pk_mul_f32 v[54:55], v[54:55], v[156:157] op_sel_hi:[1,0]
	v_pk_mul_f32 v[48:49], v[48:49], v[154:155] op_sel_hi:[1,0]
	v_pk_mul_f32 v[50:51], v[50:51], v[154:155] op_sel_hi:[1,0]
	v_pk_mul_f32 v[36:37], v[36:37], v[156:157] op_sel_hi:[1,0]
	v_pk_mul_f32 v[38:39], v[38:39], v[156:157] op_sel_hi:[1,0]
	v_pk_mul_f32 v[32:33], v[32:33], v[154:155] op_sel_hi:[1,0]
	v_pk_mul_f32 v[34:35], v[34:35], v[154:155] op_sel_hi:[1,0]
	v_pk_mul_f32 v[20:21], v[20:21], v[156:157] op_sel_hi:[1,0]
	v_pk_mul_f32 v[22:23], v[22:23], v[156:157] op_sel_hi:[1,0]
	v_pk_mul_f32 v[16:17], v[16:17], v[154:155] op_sel_hi:[1,0]
	v_pk_mul_f32 v[18:19], v[18:19], v[154:155] op_sel_hi:[1,0]
	v_pk_mul_f32 v[4:5], v[4:5], v[156:157] op_sel_hi:[1,0]
	v_pk_mul_f32 v[6:7], v[6:7], v[156:157] op_sel_hi:[1,0]
	v_pk_mul_f32 v[0:1], v[0:1], v[154:155] op_sel_hi:[1,0]
	v_pk_mul_f32 v[2:3], v[2:3], v[154:155] op_sel_hi:[1,0]
	v_pk_mul_f32 v[120:121], v[120:121], v[200:201]
	v_pk_mul_f32 v[122:123], v[122:123], v[202:203]
	v_pk_mul_f32 v[124:125], v[124:125], v[200:201]
	v_pk_mul_f32 v[126:127], v[126:127], v[202:203]
	v_cvt_pk_bf16_f32 v120, v120, v121
	v_cvt_pk_bf16_f32 v121, v122, v123
	v_lshl_add_u64 v[122:123], s[20:21], 1, v[158:159]
	v_pk_mul_f32 v[116:117], v[200:201], v[116:117]
	v_pk_mul_f32 v[118:119], v[202:203], v[118:119]
	v_cvt_pk_bf16_f32 v124, v124, v125
	v_cvt_pk_bf16_f32 v125, v126, v127
	v_cvt_pk_bf16_f32 v116, v116, v117
	v_cvt_pk_bf16_f32 v117, v118, v119
	v_lshl_add_u64 v[118:119], v[122:123], 0, s[84:85]
	v_pk_mul_f32 v[112:113], v[200:201], v[112:113]
	v_pk_mul_f32 v[114:115], v[202:203], v[114:115]
	flat_store_dwordx2 v[158:159], v[124:125]
	flat_store_dwordx2 v[122:123], v[120:121]
	flat_store_dwordx2 v[118:119], v[116:117]
	v_cvt_pk_bf16_f32 v112, v112, v113
	v_cvt_pk_bf16_f32 v113, v114, v115
	v_lshl_add_u64 v[116:117], v[118:119], 0, s[84:85]
	flat_store_dwordx2 v[116:117], v[112:113]
	v_pk_mul_f32 v[104:105], v[104:105], v[204:205]
	v_pk_mul_f32 v[106:107], v[106:107], v[206:207]
	v_cvt_pk_bf16_f32 v104, v104, v105
	v_cvt_pk_bf16_f32 v105, v106, v107
	flat_store_dwordx2 v[158:159], v[104:105] offset:512
	v_pk_mul_f32 v[104:105], v[108:109], v[150:151] op_sel_hi:[1,0]
	v_pk_mul_f32 v[106:107], v[110:111], v[150:151] op_sel_hi:[1,0]
	v_pk_mul_f32 v[104:105], v[104:105], v[204:205]
	v_pk_mul_f32 v[106:107], v[106:107], v[206:207]
	v_cvt_pk_bf16_f32 v104, v104, v105
	v_cvt_pk_bf16_f32 v105, v106, v107
	v_lshl_add_u64 v[106:107], v[116:117], 0, s[2:3]
	v_pk_mul_f32 v[100:101], v[100:101], v[204:205]
	v_pk_mul_f32 v[102:103], v[102:103], v[206:207]
	v_cvt_pk_bf16_f32 v100, v100, v101
	v_cvt_pk_bf16_f32 v101, v102, v103
	v_lshl_add_u64 v[102:103], v[106:107], 0, s[84:85]
	v_pk_mul_f32 v[96:97], v[204:205], v[96:97]
	v_pk_mul_f32 v[98:99], v[206:207], v[98:99]
	flat_store_dwordx2 v[106:107], v[104:105] offset:512
	flat_store_dwordx2 v[102:103], v[100:101] offset:512
	v_cvt_pk_bf16_f32 v96, v96, v97
	v_cvt_pk_bf16_f32 v97, v98, v99
	v_lshl_add_u64 v[100:101], v[102:103], 0, s[84:85]
	flat_store_dwordx2 v[100:101], v[96:97] offset:512
	v_pk_mul_f32 v[80:81], v[80:81], v[208:209]
	v_pk_mul_f32 v[82:83], v[82:83], v[210:211]
	v_cvt_pk_bf16_f32 v80, v80, v81
	v_cvt_pk_bf16_f32 v81, v82, v83
	flat_store_dwordx2 v[158:159], v[80:81] offset:1024
	v_pk_mul_f32 v[80:81], v[92:93], v[150:151] op_sel_hi:[1,0]
	v_pk_mul_f32 v[82:83], v[94:95], v[150:151] op_sel_hi:[1,0]
	v_pk_mul_f32 v[80:81], v[80:81], v[208:209]
	v_pk_mul_f32 v[82:83], v[82:83], v[210:211]
	v_cvt_pk_bf16_f32 v80, v80, v81
	v_cvt_pk_bf16_f32 v81, v82, v83
	v_lshl_add_u64 v[82:83], v[100:101], 0, s[2:3]
	flat_store_dwordx2 v[82:83], v[80:81] offset:1024
	v_pk_mul_f32 v[80:81], v[84:85], v[156:157] op_sel_hi:[1,0]
	v_pk_mul_f32 v[84:85], v[86:87], v[156:157] op_sel_hi:[1,0]
	v_pk_mul_f32 v[80:81], v[80:81], v[208:209]
	v_pk_mul_f32 v[84:85], v[84:85], v[210:211]
	v_cvt_pk_bf16_f32 v80, v80, v81
	v_cvt_pk_bf16_f32 v81, v84, v85
	v_lshl_add_u64 v[82:83], v[82:83], 0, s[84:85]
	flat_store_dwordx2 v[82:83], v[80:81] offset:1024
	v_pk_mul_f32 v[80:81], v[88:89], v[154:155] op_sel_hi:[1,0]
	v_pk_mul_f32 v[84:85], v[90:91], v[154:155] op_sel_hi:[1,0]
	v_pk_mul_f32 v[80:81], v[80:81], v[208:209]
	v_pk_mul_f32 v[84:85], v[84:85], v[210:211]
	v_cvt_pk_bf16_f32 v80, v80, v81
	v_cvt_pk_bf16_f32 v81, v84, v85
	v_lshl_add_u64 v[84:85], v[82:83], 0, s[84:85]
	flat_store_dwordx2 v[84:85], v[80:81] offset:1024
	v_pk_mul_f32 v[64:65], v[64:65], v[212:213]
; DI unsigned pk2(float lo, float hi) { f32x2 v = {lo, hi}; bf16x2_t b = __builtin_convertvector(v, bf16x2_t); return __builtin_bit_cast(unsigned, b); }
; DI void rms_rows4_to_bf16(const float* xb, size_t xstride, const float* g, bf16_t* ob, size_t ostride, int lane) {
;     ...
;     for (int j = 0; j < 8; ++j) { const f32x4 gg = gr[64 * j];
; #pragma unroll
;         for (int r = 0; r < 4; ++r) { u32x2 w; w.x = pk2(v[r][j].x * ss[r] * gg.x, v[r][j].y * ss[r] * gg.y); w.y = pk2(v[r][j].z * ss[r] * gg.z, v[r][j].w * ss[r] * gg.w);
;             ((u32x2*)(ob + r * ostride))[lane + 64 * j] = w; } }
; }
	v_pk_mul_f32 v[66:67], v[66:67], v[214:215]
	v_cvt_pk_bf16_f32 v64, v64, v65
	v_cvt_pk_bf16_f32 v65, v66, v67
	flat_store_dwordx2 v[158:159], v[64:65] offset:1536
	v_pk_mul_f32 v[64:65], v[68:69], v[150:151] op_sel_hi:[1,0]
	v_pk_mul_f32 v[66:67], v[70:71], v[150:151] op_sel_hi:[1,0]
	v_pk_mul_f32 v[64:65], v[64:65], v[212:213]
	v_pk_mul_f32 v[66:67], v[66:67], v[214:215]
	v_cvt_pk_bf16_f32 v64, v64, v65
	v_cvt_pk_bf16_f32 v65, v66, v67
	v_lshl_add_u64 v[66:67], v[84:85], 0, s[2:3]
	flat_store_dwordx2 v[66:67], v[64:65] offset:1536
	v_pk_mul_f32 v[64:65], v[72:73], v[156:157] op_sel_hi:[1,0]
	v_pk_mul_f32 v[68:69], v[74:75], v[156:157] op_sel_hi:[1,0]
	v_pk_mul_f32 v[64:65], v[64:65], v[212:213]
	v_pk_mul_f32 v[68:69], v[68:69], v[214:215]
	v_cvt_pk_bf16_f32 v64, v64, v65
	v_cvt_pk_bf16_f32 v65, v68, v69
	v_lshl_add_u64 v[66:67], v[66:67], 0, s[84:85]
	flat_store_dwordx2 v[66:67], v[64:65] offset:1536
	v_pk_mul_f32 v[64:65], v[76:77], v[154:155] op_sel_hi:[1,0]
	v_pk_mul_f32 v[68:69], v[78:79], v[154:155] op_sel_hi:[1,0]
	v_pk_mul_f32 v[64:65], v[64:65], v[212:213]
	v_pk_mul_f32 v[68:69], v[68:69], v[214:215]
	v_cvt_pk_bf16_f32 v64, v64, v65
	v_cvt_pk_bf16_f32 v65, v68, v69
	v_lshl_add_u64 v[68:69], v[66:67], 0, s[84:85]
	flat_store_dwordx2 v[68:69], v[64:65] offset:1536
	v_pk_mul_f32 v[56:57], v[56:57], v[216:217]
	v_pk_mul_f32 v[58:59], v[58:59], v[218:219]
	v_cvt_pk_bf16_f32 v56, v56, v57
	v_cvt_pk_bf16_f32 v57, v58, v59
	flat_store_dwordx2 v[158:159], v[56:57] offset:2048
	v_pk_mul_f32 v[56:57], v[60:61], v[150:151] op_sel_hi:[1,0]
	v_pk_mul_f32 v[58:59], v[62:63], v[150:151] op_sel_hi:[1,0]
	v_pk_mul_f32 v[56:57], v[56:57], v[216:217]
	v_pk_mul_f32 v[58:59], v[58:59], v[218:219]
	v_cvt_pk_bf16_f32 v56, v56, v57
	v_cvt_pk_bf16_f32 v57, v58, v59
	v_lshl_add_u64 v[58:59], v[68:69], 0, s[2:3]
	v_pk_mul_f32 v[52:53], v[52:53], v[216:217]
	v_pk_mul_f32 v[54:55], v[54:55], v[218:219]
	v_cvt_pk_bf16_f32 v52, v52, v53
	v_cvt_pk_bf16_f32 v53, v54, v55
	v_lshl_add_u64 v[54:55], v[58:59], 0, s[84:85]
	v_pk_mul_f32 v[48:49], v[48:49], v[216:217]
	v_pk_mul_f32 v[50:51], v[50:51], v[218:219]
	flat_store_dwordx2 v[58:59], v[56:57] offset:2048
	flat_store_dwordx2 v[54:55], v[52:53] offset:2048
	v_cvt_pk_bf16_f32 v48, v48, v49
	v_cvt_pk_bf16_f32 v49, v50, v51
	v_lshl_add_u64 v[52:53], v[54:55], 0, s[84:85]
	flat_store_dwordx2 v[52:53], v[48:49] offset:2048
	v_pk_mul_f32 v[40:41], v[40:41], v[220:221]
	v_pk_mul_f32 v[42:43], v[42:43], v[222:223]
	v_cvt_pk_bf16_f32 v40, v40, v41
	v_cvt_pk_bf16_f32 v41, v42, v43
	flat_store_dwordx2 v[158:159], v[40:41] offset:2560
	v_pk_mul_f32 v[40:41], v[44:45], v[150:151] op_sel_hi:[1,0]
	v_pk_mul_f32 v[42:43], v[46:47], v[150:151] op_sel_hi:[1,0]
	v_pk_mul_f32 v[40:41], v[40:41], v[220:221]
	v_pk_mul_f32 v[42:43], v[42:43], v[222:223]
	v_cvt_pk_bf16_f32 v40, v40, v41
	v_cvt_pk_bf16_f32 v41, v42, v43
	v_lshl_add_u64 v[42:43], v[52:53], 0, s[2:3]
	v_pk_mul_f32 v[36:37], v[36:37], v[220:221]
	v_pk_mul_f32 v[38:39], v[38:39], v[222:223]
	v_cvt_pk_bf16_f32 v36, v36, v37
	v_cvt_pk_bf16_f32 v37, v38, v39
	v_lshl_add_u64 v[38:39], v[42:43], 0, s[84:85]
	v_pk_mul_f32 v[32:33], v[32:33], v[220:221]
	v_pk_mul_f32 v[34:35], v[34:35], v[222:223]
	flat_store_dwordx2 v[42:43], v[40:41] offset:2560
	flat_store_dwordx2 v[38:39], v[36:37] offset:2560
	v_cvt_pk_bf16_f32 v32, v32, v33
	v_cvt_pk_bf16_f32 v33, v34, v35
	v_lshl_add_u64 v[36:37], v[38:39], 0, s[84:85]
	flat_store_dwordx2 v[36:37], v[32:33] offset:2560
	v_pk_mul_f32 v[24:25], v[24:25], v[224:225]
	v_pk_mul_f32 v[26:27], v[26:27], v[226:227]
	v_cvt_pk_bf16_f32 v24, v24, v25
	v_cvt_pk_bf16_f32 v25, v26, v27
	flat_store_dwordx2 v[158:159], v[24:25] offset:3072
	v_pk_mul_f32 v[24:25], v[28:29], v[150:151] op_sel_hi:[1,0]
	v_pk_mul_f32 v[26:27], v[30:31], v[150:151] op_sel_hi:[1,0]
	v_pk_mul_f32 v[24:25], v[24:25], v[224:225]
	v_pk_mul_f32 v[26:27], v[26:27], v[226:227]
	v_cvt_pk_bf16_f32 v24, v24, v25
	v_cvt_pk_bf16_f32 v25, v26, v27
	v_lshl_add_u64 v[26:27], v[36:37], 0, s[2:3]
	v_pk_mul_f32 v[20:21], v[20:21], v[224:225]
	v_pk_mul_f32 v[22:23], v[22:23], v[226:227]
	v_cvt_pk_bf16_f32 v20, v20, v21
	v_cvt_pk_bf16_f32 v21, v22, v23
	v_lshl_add_u64 v[22:23], v[26:27], 0, s[84:85]
	v_pk_mul_f32 v[16:17], v[16:17], v[224:225]
	v_pk_mul_f32 v[18:19], v[18:19], v[226:227]
	flat_store_dwordx2 v[26:27], v[24:25] offset:3072
	flat_store_dwordx2 v[22:23], v[20:21] offset:3072
	v_cvt_pk_bf16_f32 v16, v16, v17
	v_cvt_pk_bf16_f32 v17, v18, v19
	v_lshl_add_u64 v[20:21], v[22:23], 0, s[84:85]
	flat_store_dwordx2 v[20:21], v[16:17] offset:3072
	v_pk_mul_f32 v[8:9], v[8:9], v[228:229]
	v_pk_mul_f32 v[10:11], v[10:11], v[230:231]
	v_cvt_pk_bf16_f32 v8, v8, v9
	v_cvt_pk_bf16_f32 v9, v10, v11
	flat_store_dwordx2 v[158:159], v[8:9] offset:3584
	v_pk_mul_f32 v[8:9], v[12:13], v[150:151] op_sel_hi:[1,0]
	v_pk_mul_f32 v[10:11], v[14:15], v[150:151] op_sel_hi:[1,0]
	v_pk_mul_f32 v[8:9], v[8:9], v[228:229]
	v_pk_mul_f32 v[10:11], v[10:11], v[230:231]
	v_cvt_pk_bf16_f32 v8, v8, v9
	v_cvt_pk_bf16_f32 v9, v10, v11
	v_lshl_add_u64 v[10:11], v[20:21], 0, s[2:3]
	v_pk_mul_f32 v[4:5], v[4:5], v[228:229]
	v_pk_mul_f32 v[6:7], v[6:7], v[230:231]
	v_cvt_pk_bf16_f32 v4, v4, v5
	v_cvt_pk_bf16_f32 v5, v6, v7
	v_lshl_add_u64 v[6:7], v[10:11], 0, s[84:85]
	v_pk_mul_f32 v[0:1], v[0:1], v[228:229]
	v_pk_mul_f32 v[2:3], v[2:3], v[230:231]
	v_cvt_pk_bf16_f32 v0, v0, v1
	v_cvt_pk_bf16_f32 v1, v2, v3
	v_lshl_add_u64 v[2:3], v[6:7], 0, s[84:85]
	flat_store_dwordx2 v[10:11], v[8:9] offset:3584
	flat_store_dwordx2 v[6:7], v[4:5] offset:3584
	flat_store_dwordx2 v[2:3], v[0:1] offset:3584
	s_branch .LBB0_70

; DI void rms_rows4_to_bf16(const float* xb, size_t xstride, const float* g, bf16_t* ob, size_t ostride, int lane) {
;     f32x4 v[4][8]; float ss[4];
; #pragma unroll
;     for (int r = 0; r < 4; ++r)
; #pragma unroll
;         for (int j = 0; j < 8; ++j) v[r][j] = ((const f32x4*)(xb + r * xstride))[lane + 64 * j];
; #pragma unroll
;     for (int r = 0; r < 4; ++r) { float s = 0.f;
; #pragma unroll
;         for (int j = 0; j < 8; ++j) s += (v[r][j].x * v[r][j].x + v[r][j].y * v[r][j].y) + (v[r][j].z * v[r][j].z + v[r][j].w * v[r][j].w);
;         ss[r] = rsqrtf(wave_sum(s) * (1.f / D_) + EPS_); }
; __global__ void __launch_bounds__(512, 2) fwd_megakernel(Args args) {
;     ...
;         for (int m = gw; m < T_; m += 4 * NGW) {
;             if (m + 3 * NGW < T_) rms_rows4_to_bf16(out + (size_t)m * D_, (size_t)NGW * D_, norm2_g, A + (size_t)m * D_, (size_t)NGW * D_, lane);
;             else for (int mm = m; mm < T_; mm += NGW) rms_row_to_bf16(out + (size_t)mm * D_, norm2_g, A + (size_t)mm * D_, lane);
.LBB0_1455:
	s_and_b64 vcc, exec, s[2:3]
	s_cbranch_vccz .LBB0_1451
	s_ashr_i32 s1, s0, 31
	s_lshl_b64 s[2:3], s[0:1], 13
	s_add_u32 s2, s62, s2
	s_addc_u32 s3, s63, s3
	global_load_dwordx4 v[112:115], v149, s[2:3]
	global_load_dwordx4 v[96:99], v149, s[2:3] offset:1024
	global_load_dwordx4 v[80:83], v149, s[2:3] offset:2048
	global_load_dwordx4 v[64:67], v149, s[2:3] offset:3072
	global_load_dwordx4 v[60:63], v151, s[2:3]
	global_load_dwordx4 v[40:43], v153, s[2:3]
	global_load_dwordx4 v[24:27], v155, s[2:3]
	global_load_dwordx4 v[8:11], v158, s[2:3]
	s_lshl_b64 s[4:5], s[20:21], 2
	s_add_u32 s2, s2, s4
	s_addc_u32 s3, s3, s5
	global_load_dwordx4 v[116:119], v149, s[2:3]
	global_load_dwordx4 v[100:103], v149, s[2:3] offset:1024
	global_load_dwordx4 v[84:87], v149, s[2:3] offset:2048
	global_load_dwordx4 v[68:71], v149, s[2:3] offset:3072
	global_load_dwordx4 v[56:59], v151, s[2:3]
	global_load_dwordx4 v[44:47], v153, s[2:3]
	global_load_dwordx4 v[28:31], v155, s[2:3]
	global_load_dwordx4 v[12:15], v158, s[2:3]
	s_add_u32 s2, s2, s80
	s_addc_u32 s3, s3, s81
	global_load_dwordx4 v[120:123], v149, s[2:3]
	global_load_dwordx4 v[104:107], v149, s[2:3] offset:1024
	global_load_dwordx4 v[88:91], v149, s[2:3] offset:2048
	global_load_dwordx4 v[72:75], v149, s[2:3] offset:3072
	global_load_dwordx4 v[48:51], v151, s[2:3]
	global_load_dwordx4 v[36:39], v153, s[2:3]
	global_load_dwordx4 v[20:23], v155, s[2:3]
	global_load_dwordx4 v[4:7], v158, s[2:3]
	s_add_u32 s2, s2, s80
	s_addc_u32 s3, s3, s81
	global_load_dwordx4 v[124:127], v149, s[2:3]
	global_load_dwordx4 v[108:111], v149, s[2:3] offset:1024
	global_load_dwordx4 v[92:95], v149, s[2:3] offset:2048
	global_load_dwordx4 v[76:79], v149, s[2:3] offset:3072
	global_load_dwordx4 v[52:55], v151, s[2:3]
	global_load_dwordx4 v[32:35], v153, s[2:3]
	global_load_dwordx4 v[16:19], v155, s[2:3]
	global_load_dwordx4 v[0:3], v158, s[2:3]
	s_lshl_b64 s[2:3], s[0:1], 12
	global_load_dwordx4 v[200:203], v[132:133], off
	global_load_dwordx4 v[204:207], v[132:133], off offset:1024
	global_load_dwordx4 v[208:211], v[132:133], off offset:2048
	global_load_dwordx4 v[212:215], v[132:133], off offset:3072
	global_load_dwordx4 v[216:219], v[134:135], off
	global_load_dwordx4 v[220:223], v[136:137], off
	global_load_dwordx4 v[224:227], v[138:139], off
	global_load_dwordx4 v[228:231], v[140:141], off
	s_waitcnt vmcnt(0)
	v_mov_b32_e32 v130, v113
	v_mov_b32_e32 v131, v97
	v_mov_b32_e32 v128, v112
	v_mov_b32_e32 v129, v96
	v_pk_mul_f32 v[130:131], v[130:131], v[130:131]
	v_mov_b32_e32 v156, v115
	v_mov_b32_e32 v157, v99
	v_pk_fma_f32 v[128:129], v[128:129], v[128:129], v[130:131]
	v_mov_b32_e32 v130, v114
	v_mov_b32_e32 v131, v98
	v_pk_mul_f32 v[156:157], v[156:157], v[156:157]
	v_mul_f32_e32 v148, v60, v60
	v_pk_fma_f32 v[130:131], v[130:131], v[130:131], v[156:157]
	v_pk_mul_f32 v[156:157], v[80:81], v[80:81]
	v_pk_add_f32 v[128:129], v[128:129], v[130:131]
	v_pk_mul_f32 v[130:131], v[82:83], v[82:83]
	v_mul_f32_e32 v150, v61, v61
	v_pk_mov_b32 v[166:167], v[156:157], v[130:131] op_sel:[1,0]
	v_mov_b32_e32 v157, v131
	v_pk_add_f32 v[130:131], v[166:167], v[156:157]
	v_pk_add_f32 v[128:129], v[128:129], v[128:129] op_sel:[0,1] op_sel_hi:[1,0]
	v_pk_add_f32 v[130:131], v[130:131], v[130:131] op_sel:[0,1] op_sel_hi:[1,0]
	v_mov_b32_e32 v129, v148
	v_mov_b32_e32 v131, v150
	v_pk_add_f32 v[128:129], v[128:129], v[130:131]
	v_mul_f32_e32 v130, v65, v65
	v_mul_f32_e32 v148, v67, v67
	v_mul_f32_e32 v152, v62, v62
	v_mul_f32_e32 v154, v63, v63
	v_pk_fma_f32 v[130:131], v[64:65], v[64:65], v[130:131] op_sel_hi:[1,1,0]
	v_pk_fma_f32 v[156:157], v[66:67], v[66:67], v[148:149] op_sel_hi:[1,1,0]
	v_mov_b32_e32 v131, v152
	v_mov_b32_e32 v157, v154
	v_pk_add_f32 v[130:131], v[130:131], v[156:157]
	v_pk_mul_f32 v[156:157], v[40:41], v[40:41]
	v_pk_add_f32 v[128:129], v[128:129], v[130:131]
	v_pk_mul_f32 v[130:131], v[42:43], v[42:43]
	v_mul_f32_e32 v148, v8, v8
	v_pk_mov_b32 v[166:167], v[156:157], v[130:131] op_sel:[1,0]
	v_mov_b32_e32 v157, v131
	v_pk_add_f32 v[130:131], v[166:167], v[156:157]
	v_mul_f32_e32 v150, v9, v9
	v_pk_add_f32 v[128:129], v[128:129], v[128:129] op_sel:[0,1] op_sel_hi:[1,0]
	v_pk_add_f32 v[130:131], v[130:131], v[130:131] op_sel:[0,1] op_sel_hi:[1,0]
	v_mov_b32_e32 v129, v148
	v_mov_b32_e32 v131, v150
	v_pk_add_f32 v[128:129], v[128:129], v[130:131]
	v_mul_f32_e32 v130, v25, v25
	v_mul_f32_e32 v148, v27, v27
	v_mul_f32_e32 v152, v10, v10
	v_mul_f32_e32 v154, v11, v11
	v_pk_fma_f32 v[130:131], v[24:25], v[24:25], v[130:131] op_sel_hi:[1,1,0]
	v_pk_fma_f32 v[156:157], v[26:27], v[26:27], v[148:149] op_sel_hi:[1,1,0]
	v_mov_b32_e32 v131, v152
	v_mov_b32_e32 v157, v154
	v_pk_add_f32 v[130:131], v[130:131], v[156:157]
	v_mov_b32_e32 v156, v117
	v_mov_b32_e32 v157, v101
	v_pk_add_f32 v[128:129], v[128:129], v[130:131]
	v_mov_b32_e32 v130, v116
	v_mov_b32_e32 v131, v100
	v_pk_mul_f32 v[156:157], v[156:157], v[156:157]
	v_mov_b32_e32 v166, v119
	v_mov_b32_e32 v167, v103
	v_pk_fma_f32 v[130:131], v[130:131], v[130:131], v[156:157]
	v_mov_b32_e32 v156, v118
	v_mov_b32_e32 v157, v102
	v_pk_mul_f32 v[166:167], v[166:167], v[166:167]
	v_mul_f32_e32 v148, v56, v56
	v_pk_fma_f32 v[156:157], v[156:157], v[156:157], v[166:167]
	v_pk_mul_f32 v[166:167], v[84:85], v[84:85]
	v_pk_add_f32 v[130:131], v[130:131], v[156:157]
	v_pk_mul_f32 v[156:157], v[86:87], v[86:87]
	v_mul_f32_e32 v150, v57, v57
	v_pk_mov_b32 v[168:169], v[166:167], v[156:157] op_sel:[1,0]
	v_mov_b32_e32 v167, v157
	v_pk_add_f32 v[156:157], v[168:169], v[166:167]
	v_pk_add_f32 v[130:131], v[130:131], v[130:131] op_sel:[0,1] op_sel_hi:[1,0]
; DI float wave_sum(float v) {
; #pragma unroll
;     for (int o = 1; o < 64; o <<= 1) v += __shfl_xor(v, o);
;     return v;
; }
; DI void rms_rows4_to_bf16(const float* xb, size_t xstride, const float* g, bf16_t* ob, size_t ostride, int lane) {
;     ...
;     for (int r = 0; r < 4; ++r) { float s = 0.f;
; #pragma unroll
;         for (int j = 0; j < 8; ++j) s += (v[r][j].x * v[r][j].x + v[r][j].y * v[r][j].y) + (v[r][j].z * v[r][j].z + v[r][j].w * v[r][j].w);
;         ss[r] = rsqrtf(wave_sum(s) * (1.f / D_) + EPS_); }
	v_pk_add_f32 v[156:157], v[156:157], v[156:157] op_sel:[0,1] op_sel_hi:[1,0]
	v_mov_b32_e32 v131, v148
	v_mov_b32_e32 v157, v150
	v_mul_f32_e32 v148, v69, v69
	v_pk_add_f32 v[130:131], v[130:131], v[156:157]
	v_pk_fma_f32 v[156:157], v[68:69], v[68:69], v[148:149] op_sel_hi:[1,1,0]
	v_mul_f32_e32 v148, v71, v71
	v_mul_f32_e32 v152, v58, v58
	v_mul_f32_e32 v154, v59, v59
	v_pk_fma_f32 v[166:167], v[70:71], v[70:71], v[148:149] op_sel_hi:[1,1,0]
	v_mov_b32_e32 v157, v152
	v_mov_b32_e32 v167, v154
	v_pk_add_f32 v[156:157], v[156:157], v[166:167]
	v_pk_mul_f32 v[166:167], v[44:45], v[44:45]
	v_pk_add_f32 v[130:131], v[130:131], v[156:157]
	v_pk_mul_f32 v[156:157], v[46:47], v[46:47]
	v_mul_f32_e32 v148, v12, v12
	v_pk_mov_b32 v[168:169], v[166:167], v[156:157] op_sel:[1,0]
	v_mov_b32_e32 v167, v157
	v_pk_add_f32 v[156:157], v[168:169], v[166:167]
	v_mul_f32_e32 v150, v13, v13
	v_pk_add_f32 v[130:131], v[130:131], v[130:131] op_sel:[0,1] op_sel_hi:[1,0]
	v_pk_add_f32 v[156:157], v[156:157], v[156:157] op_sel:[0,1] op_sel_hi:[1,0]
	v_mov_b32_e32 v131, v148
	v_mov_b32_e32 v157, v150
	v_mul_f32_e32 v148, v29, v29
	v_pk_add_f32 v[130:131], v[130:131], v[156:157]
	v_pk_fma_f32 v[156:157], v[28:29], v[28:29], v[148:149] op_sel_hi:[1,1,0]
	v_mul_f32_e32 v148, v31, v31
	v_mul_f32_e32 v152, v14, v14
	v_mul_f32_e32 v154, v15, v15
	v_pk_fma_f32 v[166:167], v[30:31], v[30:31], v[148:149] op_sel_hi:[1,1,0]
	v_mov_b32_e32 v157, v152
	v_mov_b32_e32 v167, v154
	v_pk_add_f32 v[156:157], v[156:157], v[166:167]
	v_mov_b32_e32 v166, v123
	v_pk_add_f32 v[130:131], v[130:131], v[156:157]
	v_mov_b32_e32 v157, v128
	v_mov_b32_e32 v156, v130
	v_mov_b32_e32 v128, v131
	v_pk_add_f32 v[128:129], v[156:157], v[128:129]
	ds_bpermute_b32 v131, v193, v129
	ds_bpermute_b32 v130, v193, v128
	v_mov_b32_e32 v156, v121
	v_mov_b32_e32 v157, v105
	v_pk_mul_f32 v[156:157], v[156:157], v[156:157]
	v_mov_b32_e32 v167, v107
	s_waitcnt lgkmcnt(0)
	v_pk_add_f32 v[128:129], v[128:129], v[130:131]
	ds_bpermute_b32 v131, v194, v129
	ds_bpermute_b32 v130, v194, v128
	v_pk_mul_f32 v[166:167], v[166:167], v[166:167]
	v_mul_f32_e32 v152, v48, v48
	v_mul_f32_e32 v154, v49, v49
	v_mul_f32_e32 v159, v50, v50
	s_waitcnt lgkmcnt(0)
	v_pk_add_f32 v[128:129], v[128:129], v[130:131]
	ds_bpermute_b32 v131, v195, v129
	ds_bpermute_b32 v130, v195, v128
	v_mul_f32_e32 v160, v51, v51
	s_waitcnt lgkmcnt(0)
	v_pk_add_f32 v[128:129], v[128:129], v[130:131]
	ds_bpermute_b32 v131, v196, v129
	ds_bpermute_b32 v130, v196, v128
	s_waitcnt lgkmcnt(0)
	v_pk_add_f32 v[128:129], v[128:129], v[130:131]
	ds_bpermute_b32 v131, v197, v129
	ds_bpermute_b32 v130, v197, v128
	s_waitcnt lgkmcnt(0)
	v_pk_add_f32 v[128:129], v[128:129], v[130:131]
	ds_bpermute_b32 v131, v198, v129
	ds_bpermute_b32 v130, v198, v128
	s_waitcnt lgkmcnt(0)
	v_pk_add_f32 v[130:131], v[128:129], v[130:131]
	v_mov_b64_e32 v[128:129], s[8:9]
	v_pk_fma_f32 v[130:131], v[130:131], s[6:7], v[128:129] op_sel_hi:[1,0,0]
	s_nop 0
	v_mul_f32_e32 v148, 0x4b800000, v131
	v_cmp_gt_f32_e64 s[38:39], s97, v131
	v_cmp_gt_f32_e32 vcc, s97, v130
	s_nop 0
	v_cndmask_b32_e64 v131, v131, v148, s[38:39]
	v_rsq_f32_e32 v131, v131
	s_nop 0
	v_mul_f32_e32 v148, 0x45800000, v131
	v_cndmask_b32_e64 v150, v131, v148, s[38:39]
	v_mul_f32_e32 v131, 0x4b800000, v130
	v_cndmask_b32_e32 v130, v130, v131, vcc
	v_rsq_f32_e32 v130, v130
	v_pk_mul_f32 v[112:113], v[112:113], v[150:151] op_sel_hi:[1,0]
	v_pk_mul_f32 v[114:115], v[114:115], v[150:151] op_sel_hi:[1,0]
	v_pk_mul_f32 v[96:97], v[96:97], v[150:151] op_sel_hi:[1,0]
	v_mul_f32_e32 v131, 0x45800000, v130
	v_cndmask_b32_e32 v148, v130, v131, vcc
	v_mov_b32_e32 v130, v120
	v_mov_b32_e32 v131, v104
	v_pk_fma_f32 v[130:131], v[130:131], v[130:131], v[156:157]
	v_mov_b32_e32 v156, v122
	v_mov_b32_e32 v157, v106
	v_pk_fma_f32 v[156:157], v[156:157], v[156:157], v[166:167]
	v_pk_mul_f32 v[166:167], v[88:89], v[88:89]
	v_pk_add_f32 v[130:131], v[130:131], v[156:157]
	v_pk_mul_f32 v[156:157], v[90:91], v[90:91]
	v_pk_add_f32 v[130:131], v[130:131], v[130:131] op_sel:[0,1] op_sel_hi:[1,0]
	v_pk_mov_b32 v[168:169], v[166:167], v[156:157] op_sel:[1,0]
	v_mov_b32_e32 v167, v157
	v_pk_add_f32 v[156:157], v[168:169], v[166:167]
	v_mov_b32_e32 v131, v152
	v_pk_add_f32 v[156:157], v[156:157], v[156:157] op_sel:[0,1] op_sel_hi:[1,0]
	v_mul_f32_e32 v152, v73, v73
	v_mov_b32_e32 v157, v154
	v_pk_add_f32 v[130:131], v[130:131], v[156:157]
	v_pk_fma_f32 v[156:157], v[72:73], v[72:73], v[152:153] op_sel_hi:[1,1,0]
	v_mul_f32_e32 v152, v75, v75
	v_pk_fma_f32 v[166:167], v[74:75], v[74:75], v[152:153] op_sel_hi:[1,1,0]
	v_mov_b32_e32 v157, v159
	v_mov_b32_e32 v167, v160
	v_pk_add_f32 v[156:157], v[156:157], v[166:167]
	v_pk_mul_f32 v[166:167], v[36:37], v[36:37]
	v_pk_add_f32 v[130:131], v[130:131], v[156:157]
	v_pk_mul_f32 v[156:157], v[38:39], v[38:39]
	v_mul_f32_e32 v152, v4, v4
	v_pk_mov_b32 v[168:169], v[166:167], v[156:157] op_sel:[1,0]
	v_mov_b32_e32 v167, v157
	v_pk_add_f32 v[156:157], v[168:169], v[166:167]
	v_mul_f32_e32 v154, v5, v5
	v_pk_add_f32 v[130:131], v[130:131], v[130:131] op_sel:[0,1] op_sel_hi:[1,0]
	v_pk_add_f32 v[156:157], v[156:157], v[156:157] op_sel:[0,1] op_sel_hi:[1,0]
	v_mov_b32_e32 v131, v152
	v_mov_b32_e32 v157, v154
	v_mul_f32_e32 v152, v21, v21
	v_pk_add_f32 v[130:131], v[130:131], v[156:157]
	v_pk_fma_f32 v[156:157], v[20:21], v[20:21], v[152:153] op_sel_hi:[1,1,0]
	v_mul_f32_e32 v152, v23, v23
	v_mul_f32_e32 v159, v6, v6
	v_mul_f32_e32 v160, v7, v7
	v_pk_fma_f32 v[166:167], v[22:23], v[22:23], v[152:153] op_sel_hi:[1,1,0]
	v_mov_b32_e32 v157, v159
	v_mov_b32_e32 v167, v160
	v_pk_add_f32 v[156:157], v[156:157], v[166:167]
; DI float wave_sum(float v) {
; #pragma unroll
;     for (int o = 1; o < 64; o <<= 1) v += __shfl_xor(v, o);
;     return v;
; }
; DI void rms_rows4_to_bf16(const float* xb, size_t xstride, const float* g, bf16_t* ob, size_t ostride, int lane) {
;     ...
;     for (int r = 0; r < 4; ++r) { float s = 0.f;
; #pragma unroll
;         for (int j = 0; j < 8; ++j) s += (v[r][j].x * v[r][j].x + v[r][j].y * v[r][j].y) + (v[r][j].z * v[r][j].z + v[r][j].w * v[r][j].w);
;         ss[r] = rsqrtf(wave_sum(s) * (1.f / D_) + EPS_); }
	v_mov_b32_e32 v166, v125
	v_mov_b32_e32 v167, v109
	v_pk_add_f32 v[130:131], v[130:131], v[156:157]
	v_mov_b32_e32 v156, v124
	v_mov_b32_e32 v157, v108
	v_pk_mul_f32 v[166:167], v[166:167], v[166:167]
	v_mov_b32_e32 v168, v127
	v_mov_b32_e32 v169, v111
	v_pk_fma_f32 v[156:157], v[156:157], v[156:157], v[166:167]
	v_mov_b32_e32 v166, v126
	v_mov_b32_e32 v167, v110
	v_pk_mul_f32 v[168:169], v[168:169], v[168:169]
	v_mul_f32_e32 v152, v52, v52
	v_pk_fma_f32 v[166:167], v[166:167], v[166:167], v[168:169]
	v_pk_mul_f32 v[168:169], v[92:93], v[92:93]
	v_pk_add_f32 v[156:157], v[156:157], v[166:167]
	v_pk_mul_f32 v[166:167], v[94:95], v[94:95]
	v_mul_f32_e32 v154, v53, v53
	v_pk_mov_b32 v[170:171], v[168:169], v[166:167] op_sel:[1,0]
	v_mov_b32_e32 v169, v167
	v_pk_add_f32 v[166:167], v[170:171], v[168:169]
	v_pk_add_f32 v[156:157], v[156:157], v[156:157] op_sel:[0,1] op_sel_hi:[1,0]
	v_pk_add_f32 v[166:167], v[166:167], v[166:167] op_sel:[0,1] op_sel_hi:[1,0]
	v_mov_b32_e32 v157, v152
	v_mov_b32_e32 v167, v154
	v_mul_f32_e32 v152, v77, v77
	v_pk_add_f32 v[156:157], v[156:157], v[166:167]
	v_pk_fma_f32 v[166:167], v[76:77], v[76:77], v[152:153] op_sel_hi:[1,1,0]
	v_mul_f32_e32 v152, v79, v79
	v_mul_f32_e32 v159, v54, v54
	v_mul_f32_e32 v160, v55, v55
	v_pk_fma_f32 v[168:169], v[78:79], v[78:79], v[152:153] op_sel_hi:[1,1,0]
	v_mov_b32_e32 v167, v159
	v_mov_b32_e32 v169, v160
	v_pk_add_f32 v[166:167], v[166:167], v[168:169]
	v_pk_mul_f32 v[168:169], v[32:33], v[32:33]
	v_pk_add_f32 v[156:157], v[156:157], v[166:167]
	v_pk_mul_f32 v[166:167], v[34:35], v[34:35]
	v_mul_f32_e32 v152, v0, v0
	v_pk_mov_b32 v[170:171], v[168:169], v[166:167] op_sel:[1,0]
	v_mov_b32_e32 v169, v167
	v_pk_add_f32 v[166:167], v[170:171], v[168:169]
	v_mul_f32_e32 v154, v1, v1
	v_pk_add_f32 v[156:157], v[156:157], v[156:157] op_sel:[0,1] op_sel_hi:[1,0]
	v_pk_add_f32 v[166:167], v[166:167], v[166:167] op_sel:[0,1] op_sel_hi:[1,0]
	v_mov_b32_e32 v157, v152
	v_mov_b32_e32 v167, v154
	v_mul_f32_e32 v152, v17, v17
	v_pk_add_f32 v[156:157], v[156:157], v[166:167]
	v_pk_fma_f32 v[166:167], v[16:17], v[16:17], v[152:153] op_sel_hi:[1,1,0]
	v_mul_f32_e32 v152, v19, v19
	v_mul_f32_e32 v159, v2, v2
	v_mul_f32_e32 v160, v3, v3
	v_pk_fma_f32 v[168:169], v[18:19], v[18:19], v[152:153] op_sel_hi:[1,1,0]
	v_mov_b32_e32 v167, v159
	v_mov_b32_e32 v169, v160
	v_pk_add_f32 v[166:167], v[166:167], v[168:169]
	v_pk_mul_f32 v[98:99], v[98:99], v[150:151] op_sel_hi:[1,0]
	v_pk_add_f32 v[156:157], v[156:157], v[166:167]
	v_mov_b32_e32 v167, v130
	v_mov_b32_e32 v166, v156
	v_mov_b32_e32 v130, v157
	v_pk_add_f32 v[130:131], v[166:167], v[130:131]
	ds_bpermute_b32 v157, v193, v131
	ds_bpermute_b32 v156, v193, v130
	v_pk_mul_f32 v[80:81], v[80:81], v[150:151] op_sel_hi:[1,0]
	v_pk_mul_f32 v[82:83], v[82:83], v[150:151] op_sel_hi:[1,0]
	v_pk_mul_f32 v[64:65], v[64:65], v[150:151] op_sel_hi:[1,0]
	v_pk_mul_f32 v[66:67], v[66:67], v[150:151] op_sel_hi:[1,0]
	s_waitcnt lgkmcnt(0)
	v_pk_add_f32 v[130:131], v[130:131], v[156:157]
	ds_bpermute_b32 v157, v194, v131
	ds_bpermute_b32 v156, v194, v130
	v_pk_mul_f32 v[56:57], v[56:57], v[148:149] op_sel_hi:[1,0]
	v_pk_mul_f32 v[58:59], v[58:59], v[148:149] op_sel_hi:[1,0]
	v_pk_mul_f32 v[60:61], v[60:61], v[150:151] op_sel_hi:[1,0]
	v_pk_mul_f32 v[62:63], v[62:63], v[150:151] op_sel_hi:[1,0]
	s_waitcnt lgkmcnt(0)
	v_pk_add_f32 v[130:131], v[130:131], v[156:157]
	ds_bpermute_b32 v157, v195, v131
	ds_bpermute_b32 v156, v195, v130
	v_pk_mul_f32 v[40:41], v[40:41], v[150:151] op_sel_hi:[1,0]
	v_pk_mul_f32 v[42:43], v[42:43], v[150:151] op_sel_hi:[1,0]
	v_pk_mul_f32 v[24:25], v[24:25], v[150:151] op_sel_hi:[1,0]
	v_pk_mul_f32 v[26:27], v[26:27], v[150:151] op_sel_hi:[1,0]
	s_waitcnt lgkmcnt(0)
	v_pk_add_f32 v[130:131], v[130:131], v[156:157]
	ds_bpermute_b32 v157, v196, v131
	ds_bpermute_b32 v156, v196, v130
	v_pk_mul_f32 v[8:9], v[8:9], v[150:151] op_sel_hi:[1,0]
	v_pk_mul_f32 v[10:11], v[10:11], v[150:151] op_sel_hi:[1,0]
	s_waitcnt lgkmcnt(0)
	v_pk_add_f32 v[130:131], v[130:131], v[156:157]
	ds_bpermute_b32 v157, v197, v131
	ds_bpermute_b32 v156, v197, v130
	s_waitcnt lgkmcnt(0)
	v_pk_add_f32 v[130:131], v[130:131], v[156:157]
	ds_bpermute_b32 v157, v198, v131
	ds_bpermute_b32 v156, v198, v130
	s_waitcnt lgkmcnt(0)
; DI unsigned pk2(float lo, float hi) { f32x2 v = {lo, hi}; bf16x2_t b = __builtin_convertvector(v, bf16x2_t); return __builtin_bit_cast(unsigned, b); }
; DI void rms_rows4_to_bf16(const float* xb, size_t xstride, const float* g, bf16_t* ob, size_t ostride, int lane) {
;     ...
;         ss[r] = rsqrtf(wave_sum(s) * (1.f / D_) + EPS_); }
;     const f32x4* gr = (const f32x4*)g + lane;
; #pragma unroll
;     for (int j = 0; j < 8; ++j) { const f32x4 gg = gr[64 * j];
; #pragma unroll
;         for (int r = 0; r < 4; ++r) { u32x2 w; w.x = pk2(v[r][j].x * ss[r] * gg.x, v[r][j].y * ss[r] * gg.y); w.y = pk2(v[r][j].z * ss[r] * gg.z, v[r][j].w * ss[r] * gg.w);
;             ((u32x2*)(ob + r * ostride))[lane + 64 * j] = w; } }
	v_pk_add_f32 v[130:131], v[130:131], v[156:157]
	s_nop 0
	v_pk_fma_f32 v[128:129], v[130:131], s[6:7], v[128:129] op_sel_hi:[1,0,0]
	v_lshl_add_u64 v[156:157], v[142:143], 0, s[2:3]
	v_mul_f32_e32 v130, 0x4b800000, v129
	v_cmp_gt_f32_e64 s[38:39], s97, v129
	v_cmp_gt_f32_e32 vcc, s97, v128
	v_readlane_b32 s2, v254, 22
	v_cndmask_b32_e64 v129, v129, v130, s[38:39]
	v_rsq_f32_e32 v129, v129
	v_readlane_b32 s3, v254, 23
	v_mul_f32_e32 v130, 0x45800000, v129
	v_cndmask_b32_e64 v154, v129, v130, s[38:39]
	v_mul_f32_e32 v129, 0x4b800000, v128
	v_cndmask_b32_e32 v128, v128, v129, vcc
	v_rsq_f32_e32 v128, v128
	v_pk_mul_f32 v[48:49], v[48:49], v[154:155] op_sel_hi:[1,0]
	v_pk_mul_f32 v[50:51], v[50:51], v[154:155] op_sel_hi:[1,0]
	v_pk_mul_f32 v[36:37], v[36:37], v[154:155] op_sel_hi:[1,0]
	v_mul_f32_e32 v129, 0x45800000, v128
	v_cndmask_b32_e32 v152, v128, v129, vcc
	v_pk_mul_f32 v[38:39], v[38:39], v[154:155] op_sel_hi:[1,0]
	v_pk_mul_f32 v[32:33], v[32:33], v[152:153] op_sel_hi:[1,0]
	v_pk_mul_f32 v[34:35], v[34:35], v[152:153] op_sel_hi:[1,0]
	v_pk_mul_f32 v[20:21], v[20:21], v[154:155] op_sel_hi:[1,0]
	v_pk_mul_f32 v[22:23], v[22:23], v[154:155] op_sel_hi:[1,0]
	v_pk_mul_f32 v[16:17], v[16:17], v[152:153] op_sel_hi:[1,0]
	v_pk_mul_f32 v[18:19], v[18:19], v[152:153] op_sel_hi:[1,0]
	v_pk_mul_f32 v[4:5], v[4:5], v[154:155] op_sel_hi:[1,0]
	v_pk_mul_f32 v[6:7], v[6:7], v[154:155] op_sel_hi:[1,0]
	v_pk_mul_f32 v[0:1], v[0:1], v[152:153] op_sel_hi:[1,0]
	v_pk_mul_f32 v[2:3], v[2:3], v[152:153] op_sel_hi:[1,0]
	v_pk_mul_f32 v[112:113], v[112:113], v[200:201]
	v_pk_mul_f32 v[114:115], v[114:115], v[202:203]
	v_cvt_pk_bf16_f32 v112, v112, v113
	v_cvt_pk_bf16_f32 v113, v114, v115
	flat_store_dwordx2 v[156:157], v[112:113]
	v_pk_mul_f32 v[112:113], v[116:117], v[148:149] op_sel_hi:[1,0]
	v_pk_mul_f32 v[114:115], v[118:119], v[148:149] op_sel_hi:[1,0]
	v_pk_mul_f32 v[112:113], v[112:113], v[200:201]
	v_pk_mul_f32 v[114:115], v[114:115], v[202:203]
	v_cvt_pk_bf16_f32 v112, v112, v113
	v_cvt_pk_bf16_f32 v113, v114, v115
	v_lshl_add_u64 v[114:115], s[20:21], 1, v[156:157]
	flat_store_dwordx2 v[114:115], v[112:113]
	v_pk_mul_f32 v[112:113], v[120:121], v[154:155] op_sel_hi:[1,0]
	v_pk_mul_f32 v[116:117], v[122:123], v[154:155] op_sel_hi:[1,0]
	v_pk_mul_f32 v[112:113], v[200:201], v[112:113]
	v_pk_mul_f32 v[116:117], v[202:203], v[116:117]
	v_cvt_pk_bf16_f32 v112, v112, v113
	v_cvt_pk_bf16_f32 v113, v116, v117
	v_lshl_add_u64 v[114:115], v[114:115], 0, s[84:85]
	flat_store_dwordx2 v[114:115], v[112:113]
	v_pk_mul_f32 v[112:113], v[124:125], v[152:153] op_sel_hi:[1,0]
	v_pk_mul_f32 v[116:117], v[126:127], v[152:153] op_sel_hi:[1,0]
	v_pk_mul_f32 v[112:113], v[200:201], v[112:113]
	v_pk_mul_f32 v[116:117], v[202:203], v[116:117]
	v_cvt_pk_bf16_f32 v112, v112, v113
	v_cvt_pk_bf16_f32 v113, v116, v117
	v_lshl_add_u64 v[116:117], v[114:115], 0, s[84:85]
	flat_store_dwordx2 v[116:117], v[112:113]
	v_pk_mul_f32 v[96:97], v[96:97], v[204:205]
	v_pk_mul_f32 v[98:99], v[98:99], v[206:207]
	v_cvt_pk_bf16_f32 v96, v96, v97
	v_cvt_pk_bf16_f32 v97, v98, v99
	flat_store_dwordx2 v[156:157], v[96:97] offset:512
	v_pk_mul_f32 v[96:97], v[100:101], v[148:149] op_sel_hi:[1,0]
	v_pk_mul_f32 v[98:99], v[102:103], v[148:149] op_sel_hi:[1,0]
	v_pk_mul_f32 v[96:97], v[96:97], v[204:205]
	v_pk_mul_f32 v[98:99], v[98:99], v[206:207]
	v_cvt_pk_bf16_f32 v96, v96, v97
	v_cvt_pk_bf16_f32 v97, v98, v99
	v_lshl_add_u64 v[98:99], v[116:117], 0, s[2:3]
	flat_store_dwordx2 v[98:99], v[96:97] offset:512
	v_pk_mul_f32 v[96:97], v[104:105], v[154:155] op_sel_hi:[1,0]
	v_pk_mul_f32 v[100:101], v[106:107], v[154:155] op_sel_hi:[1,0]
	v_pk_mul_f32 v[96:97], v[96:97], v[204:205]
	v_pk_mul_f32 v[100:101], v[100:101], v[206:207]
	v_cvt_pk_bf16_f32 v96, v96, v97
	v_cvt_pk_bf16_f32 v97, v100, v101
	v_lshl_add_u64 v[98:99], v[98:99], 0, s[84:85]
	flat_store_dwordx2 v[98:99], v[96:97] offset:512
	v_pk_mul_f32 v[96:97], v[108:109], v[152:153] op_sel_hi:[1,0]
	v_pk_mul_f32 v[100:101], v[110:111], v[152:153] op_sel_hi:[1,0]
	v_pk_mul_f32 v[96:97], v[204:205], v[96:97]
	v_pk_mul_f32 v[100:101], v[206:207], v[100:101]
	v_cvt_pk_bf16_f32 v96, v96, v97
	v_cvt_pk_bf16_f32 v97, v100, v101
	v_lshl_add_u64 v[100:101], v[98:99], 0, s[84:85]
	flat_store_dwordx2 v[100:101], v[96:97] offset:512
	v_pk_mul_f32 v[80:81], v[80:81], v[208:209]
	v_pk_mul_f32 v[82:83], v[82:83], v[210:211]
	v_cvt_pk_bf16_f32 v80, v80, v81
	v_cvt_pk_bf16_f32 v81, v82, v83
	flat_store_dwordx2 v[156:157], v[80:81] offset:1024
	v_pk_mul_f32 v[80:81], v[84:85], v[148:149] op_sel_hi:[1,0]
	v_pk_mul_f32 v[82:83], v[86:87], v[148:149] op_sel_hi:[1,0]
	v_pk_mul_f32 v[80:81], v[80:81], v[208:209]
	v_pk_mul_f32 v[82:83], v[82:83], v[210:211]
	v_cvt_pk_bf16_f32 v80, v80, v81
	v_cvt_pk_bf16_f32 v81, v82, v83
	v_lshl_add_u64 v[82:83], v[100:101], 0, s[2:3]
	flat_store_dwordx2 v[82:83], v[80:81] offset:1024
	v_pk_mul_f32 v[80:81], v[88:89], v[154:155] op_sel_hi:[1,0]
	v_pk_mul_f32 v[84:85], v[90:91], v[154:155] op_sel_hi:[1,0]
	v_pk_mul_f32 v[80:81], v[80:81], v[208:209]
	v_pk_mul_f32 v[84:85], v[84:85], v[210:211]
	v_cvt_pk_bf16_f32 v80, v80, v81
	v_cvt_pk_bf16_f32 v81, v84, v85
	v_lshl_add_u64 v[82:83], v[82:83], 0, s[84:85]
	flat_store_dwordx2 v[82:83], v[80:81] offset:1024
	v_pk_mul_f32 v[80:81], v[92:93], v[152:153] op_sel_hi:[1,0]
	v_pk_mul_f32 v[84:85], v[94:95], v[152:153] op_sel_hi:[1,0]
	v_pk_mul_f32 v[80:81], v[80:81], v[208:209]
	v_pk_mul_f32 v[84:85], v[84:85], v[210:211]
	v_cvt_pk_bf16_f32 v80, v80, v81
	v_cvt_pk_bf16_f32 v81, v84, v85
	v_lshl_add_u64 v[84:85], v[82:83], 0, s[84:85]
	flat_store_dwordx2 v[84:85], v[80:81] offset:1024
; DI unsigned pk2(float lo, float hi) { f32x2 v = {lo, hi}; bf16x2_t b = __builtin_convertvector(v, bf16x2_t); return __builtin_bit_cast(unsigned, b); }
; DI void rms_rows4_to_bf16(const float* xb, size_t xstride, const float* g, bf16_t* ob, size_t ostride, int lane) {
;     ...
;     const f32x4* gr = (const f32x4*)g + lane;
; #pragma unroll
;     for (int j = 0; j < 8; ++j) { const f32x4 gg = gr[64 * j];
; #pragma unroll
;         for (int r = 0; r < 4; ++r) { u32x2 w; w.x = pk2(v[r][j].x * ss[r] * gg.x, v[r][j].y * ss[r] * gg.y); w.y = pk2(v[r][j].z * ss[r] * gg.z, v[r][j].w * ss[r] * gg.w);
;             ((u32x2*)(ob + r * ostride))[lane + 64 * j] = w; } }
	v_pk_mul_f32 v[64:65], v[64:65], v[212:213]
	v_pk_mul_f32 v[66:67], v[66:67], v[214:215]
	v_cvt_pk_bf16_f32 v64, v64, v65
	v_cvt_pk_bf16_f32 v65, v66, v67
	flat_store_dwordx2 v[156:157], v[64:65] offset:1536
	v_pk_mul_f32 v[64:65], v[68:69], v[148:149] op_sel_hi:[1,0]
	v_pk_mul_f32 v[66:67], v[70:71], v[148:149] op_sel_hi:[1,0]
	v_pk_mul_f32 v[64:65], v[64:65], v[212:213]
	v_pk_mul_f32 v[66:67], v[66:67], v[214:215]
	v_cvt_pk_bf16_f32 v64, v64, v65
	v_cvt_pk_bf16_f32 v65, v66, v67
	v_lshl_add_u64 v[66:67], v[84:85], 0, s[2:3]
	flat_store_dwordx2 v[66:67], v[64:65] offset:1536
	v_pk_mul_f32 v[64:65], v[72:73], v[154:155] op_sel_hi:[1,0]
	v_pk_mul_f32 v[68:69], v[74:75], v[154:155] op_sel_hi:[1,0]
	v_pk_mul_f32 v[64:65], v[64:65], v[212:213]
	v_pk_mul_f32 v[68:69], v[68:69], v[214:215]
	v_cvt_pk_bf16_f32 v64, v64, v65
	v_cvt_pk_bf16_f32 v65, v68, v69
	v_lshl_add_u64 v[66:67], v[66:67], 0, s[84:85]
	flat_store_dwordx2 v[66:67], v[64:65] offset:1536
	v_pk_mul_f32 v[64:65], v[76:77], v[152:153] op_sel_hi:[1,0]
	v_pk_mul_f32 v[68:69], v[78:79], v[152:153] op_sel_hi:[1,0]
	v_pk_mul_f32 v[64:65], v[64:65], v[212:213]
	v_pk_mul_f32 v[68:69], v[68:69], v[214:215]
	v_cvt_pk_bf16_f32 v64, v64, v65
	v_cvt_pk_bf16_f32 v65, v68, v69
	v_lshl_add_u64 v[68:69], v[66:67], 0, s[84:85]
	flat_store_dwordx2 v[68:69], v[64:65] offset:1536
	v_pk_mul_f32 v[56:57], v[56:57], v[216:217]
	v_pk_mul_f32 v[58:59], v[58:59], v[218:219]
	v_pk_mul_f32 v[60:61], v[60:61], v[216:217]
	v_pk_mul_f32 v[62:63], v[62:63], v[218:219]
	v_cvt_pk_bf16_f32 v56, v56, v57
	v_cvt_pk_bf16_f32 v57, v58, v59
	v_lshl_add_u64 v[58:59], v[68:69], 0, s[2:3]
	v_pk_mul_f32 v[48:49], v[48:49], v[216:217]
	v_pk_mul_f32 v[50:51], v[50:51], v[218:219]
	v_cvt_pk_bf16_f32 v60, v60, v61
	v_cvt_pk_bf16_f32 v61, v62, v63
	v_cvt_pk_bf16_f32 v48, v48, v49
	v_cvt_pk_bf16_f32 v49, v50, v51
	v_lshl_add_u64 v[50:51], v[58:59], 0, s[84:85]
	flat_store_dwordx2 v[156:157], v[60:61] offset:2048
	flat_store_dwordx2 v[58:59], v[56:57] offset:2048
	flat_store_dwordx2 v[50:51], v[48:49] offset:2048
	v_pk_mul_f32 v[48:49], v[52:53], v[152:153] op_sel_hi:[1,0]
	v_pk_mul_f32 v[52:53], v[54:55], v[152:153] op_sel_hi:[1,0]
	v_pk_mul_f32 v[48:49], v[48:49], v[216:217]
	v_pk_mul_f32 v[52:53], v[52:53], v[218:219]
	v_cvt_pk_bf16_f32 v48, v48, v49
	v_cvt_pk_bf16_f32 v49, v52, v53
	v_lshl_add_u64 v[52:53], v[50:51], 0, s[84:85]
	flat_store_dwordx2 v[52:53], v[48:49] offset:2048
	v_pk_mul_f32 v[40:41], v[40:41], v[220:221]
	v_pk_mul_f32 v[42:43], v[42:43], v[222:223]
	v_cvt_pk_bf16_f32 v40, v40, v41
	v_cvt_pk_bf16_f32 v41, v42, v43
	flat_store_dwordx2 v[156:157], v[40:41] offset:2560
	v_pk_mul_f32 v[40:41], v[44:45], v[148:149] op_sel_hi:[1,0]
	v_pk_mul_f32 v[42:43], v[46:47], v[148:149] op_sel_hi:[1,0]
	v_pk_mul_f32 v[40:41], v[40:41], v[220:221]
	v_pk_mul_f32 v[42:43], v[42:43], v[222:223]
	v_cvt_pk_bf16_f32 v40, v40, v41
	v_cvt_pk_bf16_f32 v41, v42, v43
	v_lshl_add_u64 v[42:43], v[52:53], 0, s[2:3]
	v_pk_mul_f32 v[36:37], v[36:37], v[220:221]
	v_pk_mul_f32 v[38:39], v[38:39], v[222:223]
	v_cvt_pk_bf16_f32 v36, v36, v37
	v_cvt_pk_bf16_f32 v37, v38, v39
	v_lshl_add_u64 v[38:39], v[42:43], 0, s[84:85]
	v_pk_mul_f32 v[32:33], v[32:33], v[220:221]
	v_pk_mul_f32 v[34:35], v[34:35], v[222:223]
	flat_store_dwordx2 v[42:43], v[40:41] offset:2560
	flat_store_dwordx2 v[38:39], v[36:37] offset:2560
	v_cvt_pk_bf16_f32 v32, v32, v33
	v_cvt_pk_bf16_f32 v33, v34, v35
	v_lshl_add_u64 v[36:37], v[38:39], 0, s[84:85]
	flat_store_dwordx2 v[36:37], v[32:33] offset:2560
	v_pk_mul_f32 v[24:25], v[24:25], v[224:225]
	v_pk_mul_f32 v[26:27], v[26:27], v[226:227]
	v_cvt_pk_bf16_f32 v24, v24, v25
	v_cvt_pk_bf16_f32 v25, v26, v27
	flat_store_dwordx2 v[156:157], v[24:25] offset:3072
	v_pk_mul_f32 v[24:25], v[28:29], v[148:149] op_sel_hi:[1,0]
	v_pk_mul_f32 v[26:27], v[30:31], v[148:149] op_sel_hi:[1,0]
	v_pk_mul_f32 v[24:25], v[24:25], v[224:225]
	v_pk_mul_f32 v[26:27], v[26:27], v[226:227]
	v_cvt_pk_bf16_f32 v24, v24, v25
	v_cvt_pk_bf16_f32 v25, v26, v27
	v_lshl_add_u64 v[26:27], v[36:37], 0, s[2:3]
	v_pk_mul_f32 v[20:21], v[20:21], v[224:225]
	v_pk_mul_f32 v[22:23], v[22:23], v[226:227]
	v_cvt_pk_bf16_f32 v20, v20, v21
	v_cvt_pk_bf16_f32 v21, v22, v23
	v_lshl_add_u64 v[22:23], v[26:27], 0, s[84:85]
	v_pk_mul_f32 v[16:17], v[16:17], v[224:225]
	v_pk_mul_f32 v[18:19], v[18:19], v[226:227]
	flat_store_dwordx2 v[26:27], v[24:25] offset:3072
	flat_store_dwordx2 v[22:23], v[20:21] offset:3072
	v_cvt_pk_bf16_f32 v16, v16, v17
	v_cvt_pk_bf16_f32 v17, v18, v19
	v_lshl_add_u64 v[20:21], v[22:23], 0, s[84:85]
	flat_store_dwordx2 v[20:21], v[16:17] offset:3072
	v_pk_mul_f32 v[8:9], v[8:9], v[228:229]
	v_pk_mul_f32 v[10:11], v[10:11], v[230:231]
	v_cvt_pk_bf16_f32 v8, v8, v9
	v_cvt_pk_bf16_f32 v9, v10, v11
	flat_store_dwordx2 v[156:157], v[8:9] offset:3584
	v_pk_mul_f32 v[8:9], v[12:13], v[148:149] op_sel_hi:[1,0]
	v_pk_mul_f32 v[10:11], v[14:15], v[148:149] op_sel_hi:[1,0]
	v_pk_mul_f32 v[8:9], v[8:9], v[228:229]
	v_pk_mul_f32 v[10:11], v[10:11], v[230:231]
	v_cvt_pk_bf16_f32 v8, v8, v9
	v_cvt_pk_bf16_f32 v9, v10, v11
	v_lshl_add_u64 v[10:11], v[20:21], 0, s[2:3]
	v_pk_mul_f32 v[4:5], v[4:5], v[228:229]
	v_pk_mul_f32 v[6:7], v[6:7], v[230:231]
	v_cvt_pk_bf16_f32 v4, v4, v5
	v_cvt_pk_bf16_f32 v5, v6, v7
	v_lshl_add_u64 v[6:7], v[10:11], 0, s[84:85]
	v_pk_mul_f32 v[0:1], v[0:1], v[228:229]
	v_pk_mul_f32 v[2:3], v[2:3], v[230:231]
	v_cvt_pk_bf16_f32 v0, v0, v1
	v_cvt_pk_bf16_f32 v1, v2, v3
	v_lshl_add_u64 v[2:3], v[6:7], 0, s[84:85]
	flat_store_dwordx2 v[10:11], v[8:9] offset:3584
	flat_store_dwordx2 v[6:7], v[4:5] offset:3584
	flat_store_dwordx2 v[2:3], v[0:1] offset:3584
	s_branch .LBB0_1451
